# plus: context-hyena direct-convolution loops issue their 8 filter LDS reads per 16 taps together (one wait instead of 8)
# baseline (speedup 1.0000x reference)
; __device__ __forceinline__ float bf2f(u16 h) { return __uint_as_float(((unsigned)h) << 16); }
; __device__ __forceinline__ void hyena_ctx_job(const Params& p, char* smem, int job) {
;     ...
;         for (int s = 0; s < 256; ++s) y += kf[o * 512 + t - s + 256] * zf[b * 256 + s];
;         const u16* u = UT + (size_t)gc * MTOT + MLAT + b * 256;
;         float um = t > 0 ? bf2f(u[t - 1]) : 0.f, u0 = bf2f(u[t]), up = t < 255 ? bf2f(u[t + 1]) : 0.f;
.LBB0_849:
	ds_read2_b32 v[240:241], v0 offset0:14 offset1:15
	ds_read2_b32 v[242:243], v0 offset0:12 offset1:13
	ds_read2_b32 v[244:245], v0 offset0:10 offset1:11
	ds_read2_b32 v[246:247], v0 offset0:8 offset1:9
	ds_read2_b32 v[248:249], v0 offset0:6 offset1:7
	ds_read2_b32 v[250:251], v0 offset0:4 offset1:5
	ds_read2_b32 v[252:253], v0 offset0:2 offset1:3
	ds_read2_b32 v[254:255], v0 offset1:1
	v_add_u32_e32 v38, s4, v20
	ds_read_b128 v[26:29], v38
	ds_read_b128 v[30:33], v38 offset:16
	ds_read_b128 v[34:37], v38 offset:32
	ds_read_b128 v[38:41], v38 offset:48
	s_add_i32 s4, s4, 64
	s_cmpk_eq_i32 s4, 0x400
	s_waitcnt lgkmcnt(0)
	v_fmac_f32_e32 v19, v241, v26
	v_fmac_f32_e32 v19, v240, v27
	v_fmac_f32_e32 v19, v243, v28
	v_fmac_f32_e32 v19, v242, v29
	v_fmac_f32_e32 v19, v245, v30
	v_fmac_f32_e32 v19, v244, v31
	v_fmac_f32_e32 v19, v247, v32
	v_fmac_f32_e32 v19, v246, v33
	v_fmac_f32_e32 v19, v249, v34
	v_fmac_f32_e32 v19, v248, v35
	v_fmac_f32_e32 v19, v251, v36
	v_fmac_f32_e32 v19, v250, v37
	v_fmac_f32_e32 v19, v253, v38
	v_fmac_f32_e32 v19, v252, v39
	v_fmac_f32_e32 v19, v255, v40
	v_fmac_f32_e32 v19, v254, v41
	v_subrev_u32_e32 v0, 64, v0
	s_cbranch_scc0 .LBB0_849
	s_mul_i32 s5, s18, 0x8400
	s_mul_hi_i32 s4, s18, 0x8400
	s_add_u32 s5, s2, s5
	s_addc_u32 s4, s42, s4
	s_add_u32 s26, s5, 0x8000
	s_addc_u32 s27, s4, 0
	v_lshl_add_u64 v[12:13], v[4:5], 1, s[26:27]
	v_mov_b32_e32 v26, 0
	v_lshlrev_b32_e32 v0, 1, v2
	v_mov_b32_e32 v27, 0
	s_and_saveexec_b64 s[28:29], s[38:39]
	s_cbranch_execz .LBB0_852
	v_lshl_add_u64 v[28:29], v[12:13], 0, v[0:1]
	v_add_co_u32_e64 v28, s[4:5], -2, v28
	s_nop 1
	v_addc_co_u32_e64 v29, s[4:5], -1, v29, s[4:5]
	global_load_ushort v27, v[28:29], off
	s_waitcnt vmcnt(0) lgkmcnt(0)
	v_lshlrev_b32_e32 v27, 16, v27

; __device__ __forceinline__ float bf2f(u16 h) { return __uint_as_float(((unsigned)h) << 16); }
; __device__ __forceinline__ void hyena_ctx_job(const Params& p, char* smem, int job) {
;     ...
;         for (int s = 0; s < 256; ++s) y += kf[o * 512 + t - s + 256] * zf[b * 256 + s];
;         const u16* u = UT + (size_t)gc * MTOT + MLAT + b * 256;
;         float um = t > 0 ? bf2f(u[t - 1]) : 0.f, u0 = bf2f(u[t]), up = t < 255 ? bf2f(u[t + 1]) : 0.f;
.LBB0_855:
	ds_read2_b32 v[240:241], v12 offset0:14 offset1:15
	ds_read2_b32 v[242:243], v12 offset0:12 offset1:13
	ds_read2_b32 v[244:245], v12 offset0:10 offset1:11
	ds_read2_b32 v[246:247], v12 offset0:8 offset1:9
	ds_read2_b32 v[248:249], v12 offset0:6 offset1:7
	ds_read2_b32 v[250:251], v12 offset0:4 offset1:5
	ds_read2_b32 v[252:253], v12 offset0:2 offset1:3
	ds_read2_b32 v[254:255], v12 offset1:1
	v_add_u32_e32 v13, s4, v22
	ds_read_b128 v[32:35], v13
	ds_read_b128 v[36:39], v13 offset:16
	ds_read_b128 v[40:43], v13 offset:32
	ds_read_b128 v[44:47], v13 offset:48
	s_add_i32 s4, s4, 64
	s_cmpk_lg_i32 s4, 0x400
	s_waitcnt lgkmcnt(0)
	v_fmac_f32_e32 v28, v241, v32
	v_fmac_f32_e32 v28, v240, v33
	v_fmac_f32_e32 v28, v243, v34
	v_fmac_f32_e32 v28, v242, v35
	v_fmac_f32_e32 v28, v245, v36
	v_fmac_f32_e32 v28, v244, v37
	v_fmac_f32_e32 v28, v247, v38
	v_fmac_f32_e32 v28, v246, v39
	v_fmac_f32_e32 v28, v249, v40
	v_fmac_f32_e32 v28, v248, v41
	v_fmac_f32_e32 v28, v251, v42
	v_fmac_f32_e32 v28, v250, v43
	v_fmac_f32_e32 v28, v253, v44
	v_fmac_f32_e32 v28, v252, v45
	v_fmac_f32_e32 v28, v255, v46
	v_fmac_f32_e32 v28, v254, v47
	v_subrev_u32_e32 v12, 64, v12
	s_cbranch_scc1 .LBB0_855
	v_lshl_add_u64 v[12:13], v[6:7], 1, s[26:27]
	v_mov_b32_e32 v31, 0
	v_mov_b32_e32 v32, 0
	s_and_saveexec_b64 s[26:27], s[38:39]
	s_cbranch_execz .LBB0_858
	v_lshl_add_u64 v[32:33], v[12:13], 0, v[0:1]
	v_add_co_u32_e64 v32, s[4:5], -2, v32
	s_nop 1
	v_addc_co_u32_e64 v33, s[4:5], -1, v33, s[4:5]
	global_load_ushort v32, v[32:33], off
	s_waitcnt vmcnt(0) lgkmcnt(0)
	v_lshlrev_b32_e32 v32, 16, v32

; __device__ __forceinline__ float bf2f(u16 h) { return __uint_as_float(((unsigned)h) << 16); }
; __device__ __forceinline__ void hyena_ctx_job(const Params& p, char* smem, int job) {
;     ...
;         for (int s = 0; s < 256; ++s) y += kf[o * 512 + t - s + 256] * zf[b * 256 + s];
;         const u16* u = UT + (size_t)gc * MTOT + MLAT + b * 256;
;         float um = t > 0 ? bf2f(u[t - 1]) : 0.f, u0 = bf2f(u[t]), up = t < 255 ? bf2f(u[t + 1]) : 0.f;
.LBB0_861:
	ds_read2_b32 v[240:241], v12 offset0:14 offset1:15
	ds_read2_b32 v[242:243], v12 offset0:12 offset1:13
	ds_read2_b32 v[244:245], v12 offset0:10 offset1:11
	ds_read2_b32 v[246:247], v12 offset0:8 offset1:9
	ds_read2_b32 v[248:249], v12 offset0:6 offset1:7
	ds_read2_b32 v[250:251], v12 offset0:4 offset1:5
	ds_read2_b32 v[252:253], v12 offset0:2 offset1:3
	ds_read2_b32 v[254:255], v12 offset1:1
	v_add_u32_e32 v13, s4, v20
	ds_read_b128 v[26:29], v13
	ds_read_b128 v[30:33], v13 offset:16
	ds_read_b128 v[34:37], v13 offset:32
	ds_read_b128 v[38:41], v13 offset:48
	s_add_i32 s4, s4, 64
	s_cmpk_lg_i32 s4, 0x400
	s_waitcnt lgkmcnt(0)
	v_fmac_f32_e32 v19, v241, v26
	v_fmac_f32_e32 v19, v240, v27
	v_fmac_f32_e32 v19, v243, v28
	v_fmac_f32_e32 v19, v242, v29
	v_fmac_f32_e32 v19, v245, v30
	v_fmac_f32_e32 v19, v244, v31
	v_fmac_f32_e32 v19, v247, v32
	v_fmac_f32_e32 v19, v246, v33
	v_fmac_f32_e32 v19, v249, v34
	v_fmac_f32_e32 v19, v248, v35
	v_fmac_f32_e32 v19, v251, v36
	v_fmac_f32_e32 v19, v250, v37
	v_fmac_f32_e32 v19, v253, v38
	v_fmac_f32_e32 v19, v252, v39
	v_fmac_f32_e32 v19, v255, v40
	v_fmac_f32_e32 v19, v254, v41
	v_subrev_u32_e32 v12, 64, v12
	s_cbranch_scc1 .LBB0_861
	s_add_i32 s4, s18, 0x100
	s_mul_hi_i32 s5, s4, 0x8400
	s_mul_i32 s4, s4, 0x8400
	s_add_u32 s4, s2, s4
	s_addc_u32 s5, s42, s5
	s_add_u32 s20, s4, 0x8000
	s_addc_u32 s21, s5, 0
	v_lshl_add_u64 v[12:13], v[4:5], 1, s[20:21]
	v_mov_b32_e32 v26, 0
	v_mov_b32_e32 v27, 0
	s_and_saveexec_b64 s[22:23], s[38:39]
	s_cbranch_execz .LBB0_864
	v_lshl_add_u64 v[28:29], v[12:13], 0, v[0:1]
	v_add_co_u32_e64 v28, s[4:5], -2, v28
	s_nop 1
	v_addc_co_u32_e64 v29, s[4:5], -1, v29, s[4:5]
	global_load_ushort v27, v[28:29], off
	s_waitcnt vmcnt(0) lgkmcnt(0)
	v_lshlrev_b32_e32 v27, 16, v27

; __device__ __forceinline__ float bf2f(u16 h) { return __uint_as_float(((unsigned)h) << 16); }
; __device__ __forceinline__ void hyena_ctx_job(const Params& p, char* smem, int job) {
;     ...
;         for (int s = 0; s < 256; ++s) y += kf[o * 512 + t - s + 256] * zf[b * 256 + s];
;         const u16* u = UT + (size_t)gc * MTOT + MLAT + b * 256;
;         float um = t > 0 ? bf2f(u[t - 1]) : 0.f, u0 = bf2f(u[t]), up = t < 255 ? bf2f(u[t + 1]) : 0.f;
.LBB0_867:
	ds_read2_b32 v[240:241], v12 offset0:14 offset1:15
	ds_read2_b32 v[242:243], v12 offset0:12 offset1:13
	ds_read2_b32 v[244:245], v12 offset0:10 offset1:11
	ds_read2_b32 v[246:247], v12 offset0:8 offset1:9
	ds_read2_b32 v[248:249], v12 offset0:6 offset1:7
	ds_read2_b32 v[250:251], v12 offset0:4 offset1:5
	ds_read2_b32 v[252:253], v12 offset0:2 offset1:3
	ds_read2_b32 v[254:255], v12 offset1:1
	v_add_u32_e32 v13, s4, v22
	ds_read_b128 v[32:35], v13
	ds_read_b128 v[36:39], v13 offset:16
	ds_read_b128 v[40:43], v13 offset:32
	ds_read_b128 v[44:47], v13 offset:48
	s_add_i32 s4, s4, 64
	s_cmpk_lg_i32 s4, 0x400
	s_waitcnt lgkmcnt(0)
	v_fmac_f32_e32 v28, v241, v32
	v_fmac_f32_e32 v28, v240, v33
	v_fmac_f32_e32 v28, v243, v34
	v_fmac_f32_e32 v28, v242, v35
	v_fmac_f32_e32 v28, v245, v36
	v_fmac_f32_e32 v28, v244, v37
	v_fmac_f32_e32 v28, v247, v38
	v_fmac_f32_e32 v28, v246, v39
	v_fmac_f32_e32 v28, v249, v40
	v_fmac_f32_e32 v28, v248, v41
	v_fmac_f32_e32 v28, v251, v42
	v_fmac_f32_e32 v28, v250, v43
	v_fmac_f32_e32 v28, v253, v44
	v_fmac_f32_e32 v28, v252, v45
	v_fmac_f32_e32 v28, v255, v46
	v_fmac_f32_e32 v28, v254, v47
	v_subrev_u32_e32 v12, 64, v12
	s_cbranch_scc1 .LBB0_867
	v_lshl_add_u64 v[12:13], v[6:7], 1, s[20:21]
	v_mov_b32_e32 v31, 0
	v_mov_b32_e32 v32, 0
	s_and_saveexec_b64 s[20:21], s[38:39]
	s_cbranch_execz .LBB0_870
	v_lshl_add_u64 v[32:33], v[12:13], 0, v[0:1]
	v_add_co_u32_e64 v32, s[4:5], -2, v32
	s_nop 1
	v_addc_co_u32_e64 v33, s[4:5], -1, v33, s[4:5]
	global_load_ushort v32, v[32:33], off
	s_waitcnt vmcnt(0) lgkmcnt(0)
	v_lshlrev_b32_e32 v32, 16, v32
